# phase C: wave-invariant (i,j) pair decode of the pair-factor table hoisted out of the item loop (7 scalar while-loops per item removed), 14 LDS reads batched
# speedup vs baseline: 1.0034x; 1.0034x over previous
; #define LAS __attribute__((address_space(3)))
; DI int opaque_tid() { int t = threadIdx.x; asm volatile("" : "+v"(t)); return t; }
; DI void hgrn_phase_c(const Params& p, LAS unsigned char* lds) {
;     using namespace hg;
;     unsigned char* ws = p.ws;
;     const int tid = opaque_tid(), w = tid >> 6, lane = tid & 63, dgrp = lane & 15, rsub = lane >> 4, l15 = lane & 15, g4 = lane >> 4;
;     const int wsc = __builtin_amdgcn_readfirstlane(w);
;     LAS float* Wl = (LAS float*)(lds + OFF_W); LAS float* cv = (LAS float*)(lds + OFF_CV); LAS float* part = (LAS float*)(lds + OFF_PART);
;     const bf16_t* Sg = (const bf16_t*)p.out;
;     const bf16_t* Gt = (const bf16_t*)(ws + OFF_GATE); bf16_t* Og = (bf16_t*)(ws + OFF_ABUF);
;     const f32x4 on = *(const f32x4*)(p.honorm + 16 * w + 4 * g4);
;     u32x4 gnext[4];
;     { const int it = blockIdx.x, n = it % NCHUNK, bh = it / NCHUNK, h = bh & 7, b = bh >> 3;
;       load_g4((const bf16_t*)(ws + OFF_GF) + ((size_t)b * LP + 128 * n) * D + h * DH, w, dgrp, rsub, gnext); }
.LBB0_400:
	s_or_b64 exec, exec, s[0:1]
	v_mov_b32_e32 v20, v146
	s_waitcnt lgkmcnt(0)
	s_barrier
	s_cmpk_gt_i32 s2, 0x107f
	v_ashrrev_i32_e32 v136, 6, v20
	s_nop 0
	v_readfirstlane_b32 s35, v136
	s_cbranch_scc1 .LBB0_486
	s_mul_hi_i32 s0, s2, 0x3e0f83e1
	s_lshr_b32 s1, s0, 31
	s_ashr_i32 s0, s0, 3
	s_add_i32 s3, s0, s1
	s_mul_i32 s4, s3, 33
	s_sub_i32 s4, s2, s4
	s_ashr_i32 s0, s3, 3
	s_lshl_b32 s4, s4, 7
	s_mul_hi_i32 s1, s0, 0x1080
	s_mulk_i32 s0, 0x1080
	s_ashr_i32 s5, s4, 31
	s_add_u32 s0, s0, s4
	s_addc_u32 s1, s1, s5
	s_lshl_b64 s[0:1], s[0:1], 11
	v_bfe_u32 v25, v20, 4, 2
	s_add_u32 s0, s26, s0
	v_lshlrev_b32_e32 v80, 4, v136
	v_lshlrev_b32_e32 v40, 2, v25
	s_addc_u32 s1, s27, s1
	s_lshl_b32 s3, s3, 8
	v_or_b32_e32 v22, v40, v80
	s_and_b32 s3, s3, 0x700
	v_ashrrev_i32_e32 v23, 31, v22
	s_add_u32 s0, s0, s3
	v_and_b32_e32 v137, 15, v20
	v_lshlrev_b64 v[82:83], 11, v[22:23]
	s_addc_u32 s1, s1, 0
	v_mov_b32_e32 v85, 0
	v_lshl_add_u64 v[2:3], s[0:1], 0, v[82:83]
	v_lshlrev_b32_e32 v84, 4, v137
	v_lshl_add_u64 v[2:3], v[2:3], 0, v[84:85]
	s_movk_i32 s0, 0x1000
	v_add_co_u32_e32 v26, vcc, s0, v2
	v_mov_b32_e32 v0, s48
	v_mov_b32_e32 v1, s49
	v_addc_co_u32_e32 v27, vcc, 0, v3, vcc
	v_ashrrev_i32_e32 v81, 31, v80
	global_load_dwordx4 v[16:19], v[26:27], off offset:2048 nt
	global_load_dwordx4 v[12:15], v[26:27], off nt
	global_load_dwordx4 v[8:11], v[2:3], off offset:2048 nt
	global_load_dwordx4 v[4:7], v[2:3], off nt
	v_lshl_add_u64 v[0:1], v[80:81], 2, v[0:1]
	v_lshlrev_b32_e32 v26, 4, v25
	v_mov_b32_e32 v27, v85
	v_lshl_add_u64 v[0:1], v[0:1], 0, v[26:27]
	global_load_dwordx4 v[0:3], v[0:1], off nt
	v_mbcnt_hi_u32_b32 v21, -1, v147
	v_add_u32_e32 v28, -16, v21
	v_and_b32_e32 v30, 64, v21
	v_cmp_lt_i32_e32 vcc, v28, v30
	v_or_b32_e32 v29, v137, v30
	v_mov_b32_e32 v31, 0x80
	v_cndmask_b32_e32 v28, v28, v21, vcc
	v_lshlrev_b32_e32 v138, 2, v28
	v_subrev_u32_e32 v28, 32, v21
	v_cmp_lt_i32_e32 vcc, v28, v30
	s_add_i32 s68, 0, 0x1a800
	v_lshl_or_b32 v141, v29, 2, v31
	v_cndmask_b32_e32 v28, v28, v21, vcc
	v_lshlrev_b32_e32 v139, 2, v28
	v_lshlrev_b32_e32 v28, 9, v136
	s_add_i32 s3, 0, 0x19800
	v_or_b32_e32 v31, v80, v137
	v_add_u32_e32 v42, s68, v28
	v_add_u32_e32 v43, s3, v28
	v_lshlrev_b32_e32 v28, 7, v31
	v_ashrrev_i32_e32 v29, 31, v28
	v_lshl_add_u64 v[28:29], v[28:29], 1, s[28:29]
	v_lshl_add_u64 v[90:91], v[28:29], 0, v[26:27]
	v_lshl_add_u64 v[28:29], s[30:31], 0, v[84:85]
	s_mov_b64 s[0:1], 0x19c81000
	s_add_i32 s63, 0, 0x1b800
	v_lshl_add_u64 v[92:93], v[28:29], 0, s[0:1]
	s_ashr_i32 s69, s35, 1
	v_lshlrev_b32_e32 v20, 2, v20
	s_add_i32 s0, 0, 0x1c800
	v_and_b32_e32 v20, 0x1fc, v20
	s_cmp_lt_i32 s35, 4
	v_add_u32_e32 v142, s3, v20
	v_add_u32_e32 v143, s0, v20
	s_cselect_b64 s[48:49], -1, 0
	v_lshl_or_b32 v20, s35, 5, v137
	s_movk_i32 s70, 0x110
	s_add_i32 s1, 0, 0x11000
	s_lshl_b32 s3, s35, 6
	v_mul_lo_u32 v20, v20, s70
	s_add_i32 s3, s3, s1
	v_add_u32_e32 v27, s3, v20
	v_lshlrev_b32_e32 v20, 1, v22
	v_xad_u32 v46, v20, v84, 0
	v_mul_lo_u32 v20, v31, s70
	v_add_u32_e32 v48, 0, v20
	v_xor_b32_e32 v20, 16, v21
	v_add_u32_e32 v28, 64, v30
	v_cmp_lt_i32_e32 vcc, v20, v28
	v_or_b32_e32 v32, 2, v22
	v_ashrrev_i32_e32 v33, 31, v32
	v_cndmask_b32_e32 v20, v21, v20, vcc
	v_lshlrev_b32_e32 v149, 2, v20
	v_xor_b32_e32 v20, 32, v21
	v_cmp_lt_i32_e32 vcc, v20, v28
	v_or_b32_e32 v28, 1, v22
	v_ashrrev_i32_e32 v29, 31, v28
	v_cndmask_b32_e32 v20, v21, v20, vcc
	v_lshlrev_b64 v[34:35], 10, v[32:33]
	v_or_b32_e32 v36, 3, v22
	v_lshlrev_b64 v[96:97], 11, v[32:33]
	v_or_b32_e32 v32, 2, v40
	v_lshlrev_b32_e32 v45, 3, v25
	s_mov_b32 s0, 0x11000
	v_lshlrev_b32_e32 v47, 1, v31
	v_add_u32_e32 v49, s1, v26
	v_lshlrev_b32_e32 v150, 2, v20
	v_lshlrev_b64 v[20:21], 10, v[22:23]
	v_lshlrev_b64 v[30:31], 10, v[28:29]
	v_ashrrev_i32_e32 v37, 31, v36
	v_lshlrev_b64 v[94:95], 11, v[28:29]
	v_or_b32_e32 v23, 64, v26
	v_or_b32_e32 v28, 0x80, v26
	v_or_b32_e32 v29, 0xc0, v26
	v_cmp_gt_u32_e64 s[16:17], v32, v137
	v_or_b32_e32 v32, 3, v40
	s_movk_i32 s1, 0xf0
	v_mul_u32_u24_e32 v151, 0x110, v137
	v_writelane_b32 v226, s24, 2
	v_lshlrev_b32_e32 v24, 3, v137
	v_lshl_add_u32 v41, v136, 2, s63
	v_lshlrev_b32_e32 v140, 5, v137
	v_add_u32_e32 v44, 0, v84
	v_mov_b32_e32 v80, v22
	v_lshlrev_b64 v[38:39], 10, v[36:37]
	v_mul_lo_u32 v22, v22, s70
	s_add_i32 s72, s69, 4
	s_add_i32 s74, s69, 8
	s_add_i32 s76, s69, 12
	s_add_i32 s78, s69, 16
	s_add_i32 s80, s69, 20
	s_add_i32 s82, s69, 24
	v_cmp_gt_u32_e64 s[18:19], v32, v137
	v_mul_u32_u24_e32 v32, 0x880, v137
	v_bitop3_b32 v33, v47, v26, s1 bitop3:0x6c
	v_bitop3_b32 v23, v47, v23, s1 bitop3:0x6c
	v_bitop3_b32 v28, v47, v28, s1 bitop3:0x6c
	v_bitop3_b32 v29, v47, v29, s1 bitop3:0x6c
	v_add3_u32 v152, v151, v45, s0
	s_mov_b32 s0, 0x8800
	v_writelane_b32 v226, s25, 3
	s_mov_b32 s24, s33
	s_mov_b32 s33, s94
	s_mov_b32 s61, 0
	v_lshl_add_u64 v[86:87], s[46:47], 0, v[84:85]
	v_lshl_add_u64 v[88:89], s[50:51], 0, v[84:85]
	v_cmp_eq_u32_e64 s[4:5], 0, v25
	v_cmp_lt_u32_e64 s[6:7], 1, v25
	v_cmp_eq_u32_e64 s[8:9], 3, v25
	v_cmp_eq_u32_e64 s[10:11], 2, v25
	v_or_b32_e32 v144, 0xff90, v137
	v_or_b32_e32 v145, 0xffffff80, v137
	v_add_u32_e32 v148, 0, v26
	v_lshlrev_b64 v[98:99], 11, v[36:37]
	s_lshl_b32 s71, s69, 9
	s_lshl_b32 s73, s72, 9
	s_lshl_b32 s75, s74, 9
	s_lshl_b32 s77, s76, 9
	s_lshl_b32 s79, s78, 9
	s_lshl_b32 s81, s80, 9
	s_lshl_b32 s83, s82, 9
	v_cmp_gt_u32_e64 s[12:13], v40, v137
	v_cmp_lt_u32_e64 s[14:15], v40, v137
	v_lshlrev_b32_e32 v153, 5, v25
	v_add3_u32 v154, v151, v26, s0
	v_lshlrev_b64 v[100:101], 1, v[20:21]
	v_lshlrev_b64 v[102:103], 1, v[30:31]
	v_lshlrev_b64 v[104:105], 1, v[34:35]
	v_lshlrev_b64 v[106:107], 1, v[38:39]
	v_add_u32_e32 v155, v42, v140
	v_lshlrev_b32_e32 v84, 1, v24
	v_add_u32_e32 v156, v43, v140
	s_mov_b32 s85, 0xc2e60000
	s_mov_b32 s86, 0xffff0000
	v_add_u32_e32 v157, v27, v45
	v_add_u32_e32 v158, v46, v32
	v_add_u32_e32 v159, v48, v33
	v_add_u32_e32 v160, v48, v23
	v_add_u32_e32 v161, v48, v28
	v_add_u32_e32 v162, v48, v29
	v_add_u32_e32 v163, v49, v151
	v_mov_b32_e32 v164, 0x358637bd
	s_brev_b32 s62, 60
	s_mov_b32 s87, 0x800000
	s_mov_b32 s88, 0x10000
	s_mov_b32 s89, 0x18000
	s_mov_b32 s90, 0x20000
	s_mov_b32 s91, 0x28000
	v_mov_b32_e32 v165, 0x42e60000
	v_add_u32_e32 v166, v44, v22
	v_mov_b32_e32 v176, v85
	v_mov_b32_e32 v177, v85
	v_add_u32_e32 v167, v41, v140
	s_mov_b32 s20, s2
	s_mov_b32 s0, 0
; #define LAS __attribute__((address_space(3)))
; DI void hgrn_phase_c(const Params& p, LAS unsigned char* lds) {
;     ...
;             LAS float* et = (LAS float*)(lds + OFF_ET);
;             const int dd = tid & 127;
; #pragma unroll
;             for (int k = 0; k < 7; ++k) {
;                 const int pid = (wsc >> 1) + 4 * k;
;                 int i = 1; while ((i + 1) * i / 2 <= pid) ++i;
;                 const int j = pid - i * (i - 1) / 2;
;                 et[pid * 128 + dd] = __builtin_amdgcn_exp2f(cv[i * 128 + dd] - cv[j * 128 + dd]);
;             }
.Lc_et_0:
	s_mov_b32 s1, s0
	s_add_i32 s0, s0, 1
	s_add_i32 s1, s1, 2
	s_mul_i32 s1, s1, s0
	s_lshr_b32 s3, s1, 1
	s_cmp_le_i32 s3, s69
	s_cbranch_scc1 .Lc_et_0
	s_lshl_b32 s3, s0, 1
	s_sub_i32 s1, s1, s3
	s_lshr_b32 s3, s1, 31
	s_add_i32 s1, s1, s3
	s_lshr_b32 s1, s1, 1
	s_sub_i32 s1, s69, s1
	v_lshl_add_u32 v190, s0, 9, v142
	v_lshl_add_u32 v191, s1, 9, v142
	s_mov_b32 s0, 0
.Lc_et_1:
	s_mov_b32 s1, s0
	s_add_i32 s0, s0, 1
	s_add_i32 s1, s1, 2
	s_mul_i32 s1, s1, s0
	s_lshr_b32 s3, s1, 1
	s_cmp_le_i32 s3, s72
	s_cbranch_scc1 .Lc_et_1
	s_lshl_b32 s3, s0, 1
	s_sub_i32 s1, s1, s3
	s_lshr_b32 s3, s1, 31
	s_add_i32 s1, s1, s3
	s_lshr_b32 s1, s1, 1
	s_sub_i32 s1, s72, s1
	v_lshl_add_u32 v192, s0, 9, v142
	v_lshl_add_u32 v193, s1, 9, v142
	s_mov_b32 s0, 0
.Lc_et_2:
	s_mov_b32 s1, s0
	s_add_i32 s0, s0, 1
	s_add_i32 s1, s1, 2
	s_mul_i32 s1, s1, s0
	s_lshr_b32 s3, s1, 1
	s_cmp_le_i32 s3, s74
	s_cbranch_scc1 .Lc_et_2
	s_lshl_b32 s3, s0, 1
	s_sub_i32 s1, s1, s3
	s_lshr_b32 s3, s1, 31
	s_add_i32 s1, s1, s3
	s_lshr_b32 s1, s1, 1
	s_sub_i32 s1, s74, s1
	v_lshl_add_u32 v194, s0, 9, v142
	v_lshl_add_u32 v195, s1, 9, v142
	s_mov_b32 s0, 0
.Lc_et_3:
	s_mov_b32 s1, s0
	s_add_i32 s0, s0, 1
	s_add_i32 s1, s1, 2
	s_mul_i32 s1, s1, s0
	s_lshr_b32 s3, s1, 1
	s_cmp_le_i32 s3, s76
	s_cbranch_scc1 .Lc_et_3
	s_lshl_b32 s3, s0, 1
	s_sub_i32 s1, s1, s3
	s_lshr_b32 s3, s1, 31
	s_add_i32 s1, s1, s3
	s_lshr_b32 s1, s1, 1
	s_sub_i32 s1, s76, s1
	v_lshl_add_u32 v196, s0, 9, v142
	v_lshl_add_u32 v197, s1, 9, v142
	s_mov_b32 s0, 0
.Lc_et_4:
	s_mov_b32 s1, s0
	s_add_i32 s0, s0, 1
	s_add_i32 s1, s1, 2
	s_mul_i32 s1, s1, s0
	s_lshr_b32 s3, s1, 1
	s_cmp_le_i32 s3, s78
	s_cbranch_scc1 .Lc_et_4
	s_lshl_b32 s3, s0, 1
	s_sub_i32 s1, s1, s3
	s_lshr_b32 s3, s1, 31
	s_add_i32 s1, s1, s3
	s_lshr_b32 s1, s1, 1
	s_sub_i32 s1, s78, s1
	v_lshl_add_u32 v198, s0, 9, v142
	v_lshl_add_u32 v199, s1, 9, v142
	s_mov_b32 s0, 0
.Lc_et_5:
	s_mov_b32 s1, s0
	s_add_i32 s0, s0, 1
	s_add_i32 s1, s1, 2
	s_mul_i32 s1, s1, s0
	s_lshr_b32 s3, s1, 1
	s_cmp_le_i32 s3, s80
	s_cbranch_scc1 .Lc_et_5
	s_lshl_b32 s3, s0, 1
	s_sub_i32 s1, s1, s3
	s_lshr_b32 s3, s1, 31
	s_add_i32 s1, s1, s3
	s_lshr_b32 s1, s1, 1
	s_sub_i32 s1, s80, s1
	v_lshl_add_u32 v200, s0, 9, v142
	v_lshl_add_u32 v201, s1, 9, v142
	s_mov_b32 s0, 0
.Lc_et_6:
	s_mov_b32 s1, s0
	s_add_i32 s0, s0, 1
	s_add_i32 s1, s1, 2
	s_mul_i32 s1, s1, s0
	s_lshr_b32 s3, s1, 1
	s_cmp_le_i32 s3, s82
	s_cbranch_scc1 .Lc_et_6
	s_lshl_b32 s3, s0, 1
	s_sub_i32 s1, s1, s3
	s_lshr_b32 s3, s1, 31
	s_add_i32 s1, s1, s3
	s_lshr_b32 s1, s1, 1
	s_sub_i32 s1, s82, s1
	v_lshl_add_u32 v202, s0, 9, v142
	v_lshl_add_u32 v203, s1, 9, v142
	s_branch .LBB0_403

; #define LAS __attribute__((address_space(3)))
; DI unsigned pk2(float lo, float hi) { const f32x2_t v = {lo, hi}; const bf16x2_t b = __builtin_convertvector(v, bf16x2_t); return __builtin_bit_cast(unsigned, b); }
; DI float bf_at(const u32x4& v, int j) { return __uint_as_float((j & 1) ? (v[j >> 1] & 0xffff0000u) : (v[j >> 1] << 16)); }
; DI void hgrn_phase_c(const Params& p, LAS unsigned char* lds) {
;     ...
;         u32x4 qe[4];
; #pragma unroll
;         for (int rr = 0; rr < 4; ++rr) {
;             float qp[8], kp[8], qx[8];
; #pragma unroll
;             for (int j = 0; j < 8; ++j) { const float qv = bf_at(qw[rr], j), kv = bf_at(kw[rr], j);
;                 const float t = __builtin_amdgcn_exp2f(__builtin_amdgcn_fmed3f(bb[rr][j] - cc[j], -115.f, 115.f));
;                 qp[j] = qv * t; kp[j] = kv * __builtin_amdgcn_rcpf(t); qx[j] = qp[j] * ec[j]; }
;             u32x4 a; a.x = pk2(qp[0], qp[1]); a.y = pk2(qp[2], qp[3]); a.z = pk2(qp[4], qp[5]); a.w = pk2(qp[6], qp[7]);
;             u32x4 c; c.x = pk2(kp[0], kp[1]); c.y = pk2(kp[2], kp[3]); c.z = pk2(kp[4], kp[5]); c.w = pk2(kp[6], kp[7]);
;             *(LAS u32x4*)(lds + R1 + (row0 + rr) * RS + dgrp * 16) = a;
;             *(LAS u32x4*)(lds + R2 + (row0 + rr) * RS + dgrp * 16) = c;
;             qe[rr].x = pk2(qx[0], qx[1]); qe[rr].y = pk2(qx[2], qx[3]); qe[rr].z = pk2(qx[4], qx[5]); qe[rr].w = pk2(qx[6], qx[7]);
;         }
.LBB0_419:
	s_or_b64 exec, exec, s[66:67]
	s_waitcnt lgkmcnt(7)
	v_sub_f32_e32 v56, v56, v64
	s_waitcnt lgkmcnt(6)
	v_sub_f32_e32 v57, v57, v65
	v_med3_f32 v56, v56, s85, v165
	v_med3_f32 v57, v57, s85, v165
	v_exp_f32_e32 v56, v56
	v_exp_f32_e32 v57, v57
	v_add_f32_e32 v132, v62, v126
	v_add_f32_e32 v133, v63, v127
	s_waitcnt vmcnt(7)
	v_lshlrev_b32_e32 v62, 16, v48
	v_and_b32_e32 v63, 0xffff0000, v48
	v_add_f32_e32 v130, v68, v126
	v_add_f32_e32 v131, v69, v127
	v_add_f32_e32 v126, v60, v126
	v_add_f32_e32 v127, v61, v127
	v_rcp_f32_e32 v60, v56
	v_rcp_f32_e32 v61, v57
	v_pk_mul_f32 v[68:69], v[56:57], v[62:63]
	s_waitcnt vmcnt(6)
	v_lshlrev_b32_e32 v56, 16, v44
	v_and_b32_e32 v57, 0xffff0000, v44
	s_waitcnt lgkmcnt(5)
	v_sub_f32_e32 v44, v58, v66
	v_med3_f32 v44, v44, s85, v165
	v_exp_f32_e32 v58, v44
	s_waitcnt lgkmcnt(4)
	v_sub_f32_e32 v44, v59, v67
	v_med3_f32 v44, v44, s85, v165
	v_exp_f32_e32 v59, v44
	v_pk_mul_f32 v[56:57], v[60:61], v[56:57]
	v_rcp_f32_e32 v48, v58
	v_lshlrev_b32_e32 v60, 16, v49
	v_and_b32_e32 v61, 0xffff0000, v49
	v_rcp_f32_e32 v49, v59
	v_lshlrev_b32_e32 v44, 16, v45
	v_and_b32_e32 v45, 0xffff0000, v45
	v_pk_mul_f32 v[70:71], v[58:59], v[60:61]
	v_pk_mul_f32 v[58:59], v[48:49], v[44:45]
	s_waitcnt lgkmcnt(3)
	v_sub_f32_e32 v44, v52, v128
	s_waitcnt lgkmcnt(2)
	v_sub_f32_e32 v45, v53, v129
	v_med3_f32 v44, v44, s85, v165
	v_med3_f32 v45, v45, s85, v165
	v_exp_f32_e32 v44, v44
	v_exp_f32_e32 v45, v45
	v_lshlrev_b32_e32 v52, 16, v50
	v_and_b32_e32 v53, 0xffff0000, v50
	v_rcp_f32_e32 v48, v44
	v_rcp_f32_e32 v49, v45
	v_pk_mul_f32 v[72:73], v[44:45], v[52:53]
	v_lshlrev_b32_e32 v44, 16, v46
	v_and_b32_e32 v45, 0xffff0000, v46
	v_pk_mul_f32 v[52:53], v[48:49], v[44:45]
	s_waitcnt lgkmcnt(1)
	v_sub_f32_e32 v44, v54, v169
	s_waitcnt lgkmcnt(0)
	v_sub_f32_e32 v45, v55, v170
	v_med3_f32 v44, v44, s85, v165
	v_med3_f32 v45, v45, s85, v165
	v_exp_f32_e32 v44, v44
	v_exp_f32_e32 v45, v45
	v_lshlrev_b32_e32 v50, 16, v51
	v_and_b32_e32 v51, 0xffff0000, v51
	v_rcp_f32_e32 v48, v44
	v_rcp_f32_e32 v49, v45
	v_add_f32_e32 v78, v78, v124
	v_add_f32_e32 v79, v79, v125
	v_add_f32_e32 v134, v76, v124
	v_add_f32_e32 v135, v77, v125
	v_add_f32_e32 v124, v74, v124
	v_add_f32_e32 v125, v75, v125
	v_pk_mul_f32 v[74:75], v[44:45], v[50:51]
	v_lshlrev_b32_e32 v44, 16, v47
	v_and_b32_e32 v45, 0xffff0000, v47
	v_pk_mul_f32 v[54:55], v[48:49], v[44:45]
	v_cvt_pk_bf16_f32 v44, v68, v69
	v_cvt_pk_bf16_f32 v45, v70, v71
	v_cvt_pk_bf16_f32 v46, v72, v73
	v_cvt_pk_bf16_f32 v47, v74, v75
	v_cvt_pk_bf16_f32 v48, v56, v57
	v_cvt_pk_bf16_f32 v49, v58, v59
	v_cvt_pk_bf16_f32 v50, v52, v53
	v_cvt_pk_bf16_f32 v51, v54, v55
	ds_write_b128 v166, v[44:47]
	ds_write_b128 v166, v[48:51] offset:34816
	v_sub_f32_e32 v44, v130, v64
	v_sub_f32_e32 v45, v131, v65
	v_med3_f32 v44, v44, s85, v165
	v_med3_f32 v45, v45, s85, v165
	v_exp_f32_e32 v44, v44
	v_exp_f32_e32 v45, v45
	s_waitcnt vmcnt(5)
	v_lshlrev_b32_e32 v48, 16, v40
	v_and_b32_e32 v49, 0xffff0000, v40
	v_rcp_f32_e32 v46, v44
	v_rcp_f32_e32 v47, v45
	v_pk_mul_f32 v[76:77], v[44:45], v[48:49]
	s_waitcnt vmcnt(4)
	v_lshlrev_b32_e32 v44, 16, v36
	v_and_b32_e32 v45, 0xffff0000, v36
	v_sub_f32_e32 v36, v78, v66
	v_med3_f32 v36, v36, s85, v165
	v_pk_mul_f32 v[44:45], v[46:47], v[44:45]
	v_exp_f32_e32 v46, v36
	v_sub_f32_e32 v36, v79, v67
	v_med3_f32 v36, v36, s85, v165
	v_exp_f32_e32 v47, v36
	v_rcp_f32_e32 v40, v46
	v_lshlrev_b32_e32 v48, 16, v41
	v_and_b32_e32 v49, 0xffff0000, v41
	v_rcp_f32_e32 v41, v47
	v_add_f32_e32 v112, v112, v122
	v_add_f32_e32 v113, v113, v123
	v_lshlrev_b32_e32 v36, 16, v37
	v_and_b32_e32 v37, 0xffff0000, v37
	v_pk_mul_f32 v[78:79], v[46:47], v[48:49]
	v_pk_mul_f32 v[46:47], v[40:41], v[36:37]
	v_sub_f32_e32 v36, v112, v128
	v_sub_f32_e32 v37, v113, v129
	v_med3_f32 v36, v36, s85, v165
	v_med3_f32 v37, v37, s85, v165
	v_exp_f32_e32 v36, v36
	v_exp_f32_e32 v37, v37
	v_lshlrev_b32_e32 v48, 16, v42
	v_and_b32_e32 v49, 0xffff0000, v42
	v_rcp_f32_e32 v40, v36
	v_rcp_f32_e32 v41, v37
	v_add_f32_e32 v118, v118, v120
	v_add_f32_e32 v119, v119, v121
	v_add_f32_e32 v175, v108, v122
	v_add_f32_e32 v178, v109, v123
	v_pk_mul_f32 v[108:109], v[36:37], v[48:49]
	v_lshlrev_b32_e32 v36, 16, v38
	v_and_b32_e32 v37, 0xffff0000, v38
	v_pk_mul_f32 v[48:49], v[40:41], v[36:37]
	v_sub_f32_e32 v36, v118, v169
	v_sub_f32_e32 v37, v119, v170
	v_med3_f32 v36, v36, s85, v165
	v_med3_f32 v37, v37, s85, v165
	v_exp_f32_e32 v36, v36
	v_exp_f32_e32 v37, v37
	v_lshlrev_b32_e32 v42, 16, v43
	v_and_b32_e32 v43, 0xffff0000, v43
	v_rcp_f32_e32 v40, v36
	v_rcp_f32_e32 v41, v37
	v_add_f32_e32 v171, v110, v122
	v_add_f32_e32 v172, v111, v123
	v_pk_mul_f32 v[110:111], v[36:37], v[42:43]
	v_lshlrev_b32_e32 v36, 16, v39
	v_and_b32_e32 v37, 0xffff0000, v39
	v_pk_mul_f32 v[50:51], v[40:41], v[36:37]
	v_cvt_pk_bf16_f32 v36, v76, v77
	v_cvt_pk_bf16_f32 v37, v78, v79
	v_cvt_pk_bf16_f32 v38, v108, v109
	v_cvt_pk_bf16_f32 v39, v110, v111
	v_cvt_pk_bf16_f32 v40, v44, v45
	v_cvt_pk_bf16_f32 v41, v46, v47
	v_cvt_pk_bf16_f32 v42, v48, v49
	v_cvt_pk_bf16_f32 v43, v50, v51
	ds_write_b128 v166, v[36:39] offset:272
	ds_write_b128 v166, v[40:43] offset:35088
	v_sub_f32_e32 v36, v132, v64
	v_sub_f32_e32 v37, v133, v65
	v_med3_f32 v36, v36, s85, v165
	v_med3_f32 v37, v37, s85, v165
	v_exp_f32_e32 v36, v36
	v_exp_f32_e32 v37, v37
	s_waitcnt vmcnt(3)
	v_lshlrev_b32_e32 v40, 16, v32
	v_and_b32_e32 v41, 0xffff0000, v32
	v_rcp_f32_e32 v38, v36
	v_rcp_f32_e32 v39, v37
	v_pk_mul_f32 v[112:113], v[36:37], v[40:41]
	s_waitcnt vmcnt(2)
; #define LAS __attribute__((address_space(3)))
; DI unsigned pk2(float lo, float hi) { const f32x2_t v = {lo, hi}; const bf16x2_t b = __builtin_convertvector(v, bf16x2_t); return __builtin_bit_cast(unsigned, b); }
; DI float bf_at(const u32x4& v, int j) { return __uint_as_float((j & 1) ? (v[j >> 1] & 0xffff0000u) : (v[j >> 1] << 16)); }
; DI void hgrn_phase_c(const Params& p, LAS unsigned char* lds) {
;     ...
;         for (int rr = 0; rr < 4; ++rr) {
;             float qp[8], kp[8], qx[8];
; #pragma unroll
;             for (int j = 0; j < 8; ++j) { const float qv = bf_at(qw[rr], j), kv = bf_at(kw[rr], j);
;                 const float t = __builtin_amdgcn_exp2f(__builtin_amdgcn_fmed3f(bb[rr][j] - cc[j], -115.f, 115.f));
;                 qp[j] = qv * t; kp[j] = kv * __builtin_amdgcn_rcpf(t); qx[j] = qp[j] * ec[j]; }
;             u32x4 a; a.x = pk2(qp[0], qp[1]); a.y = pk2(qp[2], qp[3]); a.z = pk2(qp[4], qp[5]); a.w = pk2(qp[6], qp[7]);
;             u32x4 c; c.x = pk2(kp[0], kp[1]); c.y = pk2(kp[2], kp[3]); c.z = pk2(kp[4], kp[5]); c.w = pk2(kp[6], kp[7]);
;             *(LAS u32x4*)(lds + R1 + (row0 + rr) * RS + dgrp * 16) = a;
;             *(LAS u32x4*)(lds + R2 + (row0 + rr) * RS + dgrp * 16) = c;
;             qe[rr].x = pk2(qx[0], qx[1]); qe[rr].y = pk2(qx[2], qx[3]); qe[rr].z = pk2(qx[4], qx[5]); qe[rr].w = pk2(qx[6], qx[7]);
;         }
;         __syncthreads();
;         bf16x8 sf[4]; u32x4 vw[4];
; #pragma unroll
;         for (int ks = 0; ks < 4; ++ks) sf[ks] = *(const bf16x8*)(St + (16 * w + l15) * 128 + 32 * ks + 8 * g4);
; #pragma unroll
;         for (int rr = 0; rr < 4; ++rr) vw[rr] = *(const u32x4*)(Vg + (size_t)(row0 + rr) * D + 8 * dgrp);
;         {
;             LAS float* et = (LAS float*)(lds + OFF_ET);
;             const int dd = tid & 127;
; #pragma unroll
;             for (int k = 0; k < 7; ++k) {
;                 const int pid = (wsc >> 1) + 4 * k;
;                 int i = 1; while ((i + 1) * i / 2 <= pid) ++i;
;                 const int j = pid - i * (i - 1) / 2;
;                 et[pid * 128 + dd] = __builtin_amdgcn_exp2f(cv[i * 128 + dd] - cv[j * 128 + dd]);
;             }
;         }
;         __syncthreads();
	v_lshlrev_b32_e32 v36, 16, v28
	v_and_b32_e32 v37, 0xffff0000, v28
	v_sub_f32_e32 v28, v134, v66
	v_med3_f32 v28, v28, s85, v165
	v_pk_mul_f32 v[36:37], v[38:39], v[36:37]
	v_exp_f32_e32 v38, v28
	v_sub_f32_e32 v28, v135, v67
	v_med3_f32 v28, v28, s85, v165
	v_exp_f32_e32 v39, v28
	v_rcp_f32_e32 v32, v38
	v_lshlrev_b32_e32 v40, 16, v33
	v_and_b32_e32 v41, 0xffff0000, v33
	v_rcp_f32_e32 v33, v39
	v_lshlrev_b32_e32 v28, 16, v29
	v_and_b32_e32 v29, 0xffff0000, v29
	v_add_f32_e32 v179, v114, v120
	v_add_f32_e32 v180, v115, v121
	v_pk_mul_f32 v[114:115], v[38:39], v[40:41]
	v_pk_mul_f32 v[38:39], v[32:33], v[28:29]
	v_sub_f32_e32 v28, v171, v128
	v_sub_f32_e32 v29, v172, v129
	v_med3_f32 v28, v28, s85, v165
	v_med3_f32 v29, v29, s85, v165
	v_exp_f32_e32 v28, v28
	v_exp_f32_e32 v29, v29
	v_lshlrev_b32_e32 v40, 16, v34
	v_and_b32_e32 v41, 0xffff0000, v34
	v_rcp_f32_e32 v32, v28
	v_rcp_f32_e32 v33, v29
	v_add_f32_e32 v173, v116, v120
	v_add_f32_e32 v174, v117, v121
	v_pk_mul_f32 v[116:117], v[28:29], v[40:41]
	v_lshlrev_b32_e32 v28, 16, v30
	v_and_b32_e32 v29, 0xffff0000, v30
	v_pk_mul_f32 v[40:41], v[32:33], v[28:29]
	v_sub_f32_e32 v28, v173, v169
	v_sub_f32_e32 v29, v174, v170
	v_med3_f32 v28, v28, s85, v165
	v_med3_f32 v29, v29, s85, v165
	v_exp_f32_e32 v28, v28
	v_exp_f32_e32 v29, v29
	v_lshlrev_b32_e32 v34, 16, v35
	v_and_b32_e32 v35, 0xffff0000, v35
	v_rcp_f32_e32 v32, v28
	v_rcp_f32_e32 v33, v29
	v_pk_mul_f32 v[118:119], v[28:29], v[34:35]
	v_lshlrev_b32_e32 v28, 16, v31
	v_and_b32_e32 v29, 0xffff0000, v31
	v_pk_mul_f32 v[42:43], v[32:33], v[28:29]
	v_cvt_pk_bf16_f32 v28, v112, v113
	v_cvt_pk_bf16_f32 v29, v114, v115
	v_cvt_pk_bf16_f32 v30, v116, v117
	v_cvt_pk_bf16_f32 v31, v118, v119
	v_cvt_pk_bf16_f32 v32, v36, v37
	v_cvt_pk_bf16_f32 v33, v38, v39
	v_cvt_pk_bf16_f32 v34, v40, v41
	v_cvt_pk_bf16_f32 v35, v42, v43
	ds_write_b128 v166, v[28:31] offset:544
	ds_write_b128 v166, v[32:35] offset:35360
	v_sub_f32_e32 v28, v126, v64
	v_sub_f32_e32 v29, v127, v65
	v_med3_f32 v28, v28, s85, v165
	v_med3_f32 v29, v29, s85, v165
	v_exp_f32_e32 v28, v28
	v_exp_f32_e32 v29, v29
	s_waitcnt vmcnt(1)
	v_lshlrev_b32_e32 v32, 16, v24
	v_and_b32_e32 v33, 0xffff0000, v24
	v_rcp_f32_e32 v30, v28
	v_rcp_f32_e32 v31, v29
	v_pk_mul_f32 v[120:121], v[28:29], v[32:33]
	s_waitcnt vmcnt(0)
	v_lshlrev_b32_e32 v28, 16, v20
	v_and_b32_e32 v29, 0xffff0000, v20
	v_sub_f32_e32 v20, v124, v66
	v_med3_f32 v20, v20, s85, v165
	v_pk_mul_f32 v[28:29], v[30:31], v[28:29]
	v_exp_f32_e32 v30, v20
	v_sub_f32_e32 v20, v125, v67
	v_med3_f32 v20, v20, s85, v165
	v_exp_f32_e32 v31, v20
	v_rcp_f32_e32 v24, v30
	v_lshlrev_b32_e32 v32, 16, v25
	v_and_b32_e32 v33, 0xffff0000, v25
	v_rcp_f32_e32 v25, v31
	v_lshlrev_b32_e32 v20, 16, v21
	v_and_b32_e32 v21, 0xffff0000, v21
	v_pk_mul_f32 v[122:123], v[30:31], v[32:33]
	v_pk_mul_f32 v[30:31], v[24:25], v[20:21]
	v_sub_f32_e32 v20, v175, v128
	v_sub_f32_e32 v21, v178, v129
	v_med3_f32 v20, v20, s85, v165
	v_med3_f32 v21, v21, s85, v165
	v_exp_f32_e32 v20, v20
	v_exp_f32_e32 v21, v21
	v_lshlrev_b32_e32 v32, 16, v26
	v_and_b32_e32 v33, 0xffff0000, v26
	v_rcp_f32_e32 v24, v20
	v_rcp_f32_e32 v25, v21
	v_pk_mul_f32 v[124:125], v[20:21], v[32:33]
	v_lshlrev_b32_e32 v20, 16, v22
	v_and_b32_e32 v21, 0xffff0000, v22
	v_pk_mul_f32 v[32:33], v[24:25], v[20:21]
	v_sub_f32_e32 v20, v179, v169
	v_sub_f32_e32 v21, v180, v170
	v_med3_f32 v20, v20, s85, v165
	v_med3_f32 v21, v21, s85, v165
	v_exp_f32_e32 v20, v20
	v_exp_f32_e32 v21, v21
	v_lshlrev_b32_e32 v26, 16, v27
	v_and_b32_e32 v27, 0xffff0000, v27
	v_rcp_f32_e32 v24, v20
	v_rcp_f32_e32 v25, v21
	s_ashr_i32 s21, s20, 31
	v_pk_mul_f32 v[126:127], v[20:21], v[26:27]
	v_lshlrev_b32_e32 v20, 16, v23
	v_and_b32_e32 v21, 0xffff0000, v23
	s_lshl_b64 s[20:21], s[20:21], 15
	v_pk_mul_f32 v[34:35], v[24:25], v[20:21]
	v_cvt_pk_bf16_f32 v20, v120, v121
	v_cvt_pk_bf16_f32 v21, v122, v123
	v_cvt_pk_bf16_f32 v22, v124, v125
	v_cvt_pk_bf16_f32 v23, v126, v127
	v_cvt_pk_bf16_f32 v24, v28, v29
	v_cvt_pk_bf16_f32 v25, v30, v31
	v_cvt_pk_bf16_f32 v26, v32, v33
	v_cvt_pk_bf16_f32 v27, v34, v35
	ds_write_b128 v166, v[20:23] offset:816
	ds_write_b128 v166, v[24:27] offset:35632
	v_lshl_add_u64 v[20:21], v[90:91], 0, s[20:21]
	s_waitcnt lgkmcnt(0)
	s_barrier
	global_load_dwordx4 v[60:63], v[20:21], off
	global_load_dwordx4 v[28:31], v[20:21], off offset:64
	global_load_dwordx4 v[24:27], v[20:21], off offset:128
	s_nop 0
	global_load_dwordx4 v[20:23], v[20:21], off offset:192
	v_lshl_add_u64 v[40:41], s[0:1], 1, v[92:93]
	v_lshl_add_u64 v[32:33], v[40:41], 0, v[82:83]
	v_lshl_add_u64 v[36:37], v[40:41], 0, v[94:95]
	v_lshl_add_u64 v[42:43], v[40:41], 0, v[96:97]
	v_lshl_add_u64 v[44:45], v[40:41], 0, v[98:99]
	global_load_dwordx4 v[32:35], v[32:33], off nt
	s_nop 0
	global_load_dwordx4 v[36:39], v[36:37], off nt
	s_nop 0
	global_load_dwordx4 v[40:43], v[42:43], off nt
	s_nop 0
	global_load_dwordx4 v[44:47], v[44:45], off nt
	v_exp_f32_e32 v130, v64
	v_exp_f32_e32 v131, v65
	v_exp_f32_e32 v132, v66
	v_exp_f32_e32 v133, v67
	v_exp_f32_e32 v134, v128
	v_exp_f32_e32 v135, v129
	v_exp_f32_e32 v128, v169
	v_exp_f32_e32 v129, v170
	ds_read_b32 v204, v190
	ds_read_b32 v205, v191
	ds_read_b32 v206, v192
	ds_read_b32 v207, v193
	ds_read_b32 v208, v194
	ds_read_b32 v209, v195
	ds_read_b32 v210, v196
	ds_read_b32 v211, v197
	ds_read_b32 v212, v198
	ds_read_b32 v213, v199
	ds_read_b32 v214, v200
	ds_read_b32 v215, v201
	ds_read_b32 v216, v202
	ds_read_b32 v217, v203
	s_mov_b32 s96, 1
	s_mov_b32 s97, 0
	v_mov_b32_e32 v169, v152
	s_mov_b32 s3, 0
	s_waitcnt lgkmcnt(0)
	v_sub_f32_e32 v204, v204, v205
	v_sub_f32_e32 v206, v206, v207
	v_sub_f32_e32 v208, v208, v209
	v_sub_f32_e32 v210, v210, v211
	v_sub_f32_e32 v212, v212, v213
	v_sub_f32_e32 v214, v214, v215
	v_sub_f32_e32 v216, v216, v217
	v_exp_f32_e32 v204, v204
	v_exp_f32_e32 v206, v206
	v_exp_f32_e32 v208, v208
	v_exp_f32_e32 v210, v210
	v_exp_f32_e32 v212, v212
	v_exp_f32_e32 v214, v214
	v_exp_f32_e32 v216, v216
	s_nop 0
	v_add_u32_e32 v205, s71, v143
	ds_write_b32 v205, v204
	v_add_u32_e32 v207, s73, v143
	ds_write_b32 v207, v206
	v_add_u32_e32 v209, s75, v143
	ds_write_b32 v209, v208
	v_add_u32_e32 v211, s77, v143
	ds_write_b32 v211, v210
	v_add_u32_e32 v213, s79, v143
	ds_write_b32 v213, v212
	v_add_u32_e32 v215, s81, v143
	ds_write_b32 v215, v214
	v_add_u32_e32 v217, s83, v143
	ds_write_b32 v217, v216
	s_waitcnt lgkmcnt(0)
	s_barrier
	s_branch .LBB0_435
